# same as previous with 4 instead of 2 wait states between the residual epilogue's wide stores and the VALU writes of their data registers (safety margin)
# baseline (speedup 1.0000x reference)
;     __device__ __forceinline__ void operator()(AccRef acc, const pg8::Unit& u, int wr, int wc, int fr, int fq) const {
;     ...
;                 for (int bj = 0; bj < 2; ++bj) xw[m][bj] = *(const v4u*)(xb + (size_t)(row0 + ai * 128 + m * 16) * D + col0 + bj * 128);
; #pragma unroll
;             for (int m = 0; m < 4; ++m) {
;                 const int row = row0 + ai * 128 + m * 16;
;                 float ss = 0.f;
; #pragma unroll
;                 for (int bj = 0; bj < 2; ++bj) {
;                     const size_t p = (size_t)row * D + col0 + bj * 128;
;                     const v4u w0 = xw[m][bj];
;                     f32x4 a = {bflo(w0.x), bfhi(w0.x), bflo(w0.y), bfhi(w0.y)}, b = {bflo(w0.z), bfhi(w0.z), bflo(w0.w), bfhi(w0.w)};
;                     a = a + acc[ai][bj][m][0] * scale; b = b + acc[ai][bj][m][1] * scale;
;                     if (outf) { *(f32x4*)(outf + p) = a; *(f32x4*)(outf + p + 4) = b; }
.LBB0_426:
	v_add_u32_e32 v54, 0x80, v42
	v_ashrrev_i32_e32 v55, 31, v54
	v_add_u32_e32 v50, 0x90, v42
	s_waitcnt lgkmcnt(0)
	v_lshlrev_b64 v[2:3], 11, v[54:55]
	v_ashrrev_i32_e32 v51, 31, v50
	v_add_u32_e32 v46, 0xa0, v42
	v_lshl_add_u64 v[56:57], v[38:39], 0, v[2:3]
	v_lshlrev_b64 v[2:3], 11, v[50:51]
	v_ashrrev_i32_e32 v47, 31, v46
	v_add_u32_e32 v42, 0xb0, v42
	v_lshl_add_u64 v[52:53], v[38:39], 0, v[2:3]
	v_lshlrev_b64 v[2:3], 11, v[46:47]
	v_ashrrev_i32_e32 v43, 31, v42
	v_lshl_add_u64 v[48:49], v[38:39], 0, v[2:3]
	v_lshlrev_b64 v[2:3], 11, v[42:43]
	v_mov_b64_e32 v[30:31], v[194:195]
	v_mov_b64_e32 v[32:33], v[196:197]
	v_mov_b64_e32 v[26:27], v[198:199]
	v_mov_b64_e32 v[28:29], v[200:201]
	v_lshl_add_u64 v[44:45], v[38:39], 0, v[2:3]
	v_mov_b64_e32 v[22:23], v[202:203]
	v_mov_b64_e32 v[24:25], v[204:205]
	v_mov_b64_e32 v[18:19], v[206:207]
	v_mov_b64_e32 v[20:21], v[208:209]
	v_mov_b64_e32 v[14:15], v[210:211]
	v_mov_b64_e32 v[16:17], v[212:213]
	v_mov_b64_e32 v[10:11], v[224:225]
	v_mov_b64_e32 v[12:13], v[226:227]
	v_mov_b64_e32 v[6:7], v[228:229]
	v_mov_b64_e32 v[8:9], v[230:231]
	global_load_dwordx4 v[2:5], v[44:45], off offset:256
	v_lshlrev_b64 v[60:61], 10, v[54:55]
	v_lshl_add_u64 v[58:59], v[60:61], 0, v[40:41]
	s_mov_b64 s[12:13], -1
	s_and_b64 vcc, exec, s[6:7]
	v_lshl_add_u64 v[58:59], v[58:59], 2, s[54:55]
	s_nop 3
	v_lshlrev_b32_e32 v34, 16, v30
	v_and_b32_e32 v35, 0xffff0000, v30
	v_lshlrev_b32_e32 v30, 16, v31
	v_and_b32_e32 v31, 0xffff0000, v31
	v_lshlrev_b32_e32 v62, 16, v32
	v_and_b32_e32 v63, 0xffff0000, v32
	v_lshlrev_b32_e32 v32, 16, v33
	v_and_b32_e32 v33, 0xffff0000, v33
	v_pk_fma_f32 v[36:37], s[72:73], v[128:129], v[30:31]
	v_pk_fma_f32 v[34:35], s[52:53], v[126:127], v[34:35]
	v_pk_fma_f32 v[32:33], s[72:73], v[124:125], v[32:33]
	v_pk_fma_f32 v[30:31], s[52:53], v[122:123], v[62:63]
	s_cbranch_vccnz .LBB0_428
	s_mov_b64 s[12:13], 0
	global_store_dwordx4 v[58:59], v[34:37], off
	global_store_dwordx4 v[58:59], v[30:33], off offset:16

;     __device__ __forceinline__ void operator()(AccRef acc, const pg8::Unit& u, int wr, int wc, int fr, int fq) const {
;     ...
;                     const size_t p = (size_t)row * D + col0 + bj * 128;
;                     const v4u w0 = xw[m][bj];
;                     f32x4 a = {bflo(w0.x), bfhi(w0.x), bflo(w0.y), bfhi(w0.y)}, b = {bflo(w0.z), bfhi(w0.z), bflo(w0.w), bfhi(w0.w)};
;                     a = a + acc[ai][bj][m][0] * scale; b = b + acc[ai][bj][m][1] * scale;
;                     if (outf) { *(f32x4*)(outf + p) = a; *(f32x4*)(outf + p + 4) = b; }
.LBB0_430:
	s_nop 3
	v_lshlrev_b32_e32 v30, 16, v26
	v_and_b32_e32 v31, 0xffff0000, v26
	v_lshlrev_b32_e32 v26, 16, v27
	v_and_b32_e32 v27, 0xffff0000, v27
	v_lshlrev_b32_e32 v34, 16, v28
	v_and_b32_e32 v35, 0xffff0000, v28
	v_lshlrev_b32_e32 v32, 16, v29
	v_and_b32_e32 v33, 0xffff0000, v29
	v_pk_fma_f32 v[28:29], s[72:73], v[120:121], v[26:27]
	v_pk_fma_f32 v[26:27], s[52:53], v[118:119], v[30:31]
	v_pk_fma_f32 v[32:33], s[72:73], v[116:117], v[32:33]
	v_pk_fma_f32 v[30:31], s[52:53], v[114:115], v[34:35]
	s_and_b64 vcc, exec, s[6:7]
	s_mov_b64 s[12:13], -1
	s_cbranch_vccnz .LBB0_433
	global_store_dwordx4 v[58:59], v[26:29], off offset:512
	global_store_dwordx4 v[58:59], v[30:33], off offset:528
	s_cbranch_execz .LBB0_434

;     __device__ __forceinline__ void operator()(AccRef acc, const pg8::Unit& u, int wr, int wc, int fr, int fq) const {
;     ...
;                     const size_t p = (size_t)row * D + col0 + bj * 128;
;                     const v4u w0 = xw[m][bj];
;                     f32x4 a = {bflo(w0.x), bfhi(w0.x), bflo(w0.y), bfhi(w0.y)}, b = {bflo(w0.z), bfhi(w0.z), bflo(w0.w), bfhi(w0.w)};
;                     a = a + acc[ai][bj][m][0] * scale; b = b + acc[ai][bj][m][1] * scale;
;                     if (outf) { *(f32x4*)(outf + p) = a; *(f32x4*)(outf + p + 4) = b; }
.LBB0_438:
	v_lshlrev_b64 v[32:33], 10, v[50:51]
	v_lshl_add_u64 v[30:31], v[32:33], 0, v[40:41]
	s_nop 3
	v_lshlrev_b32_e32 v26, 16, v22
	s_waitcnt lgkmcnt(0)
	v_and_b32_e32 v27, 0xffff0000, v22
	v_lshlrev_b32_e32 v22, 16, v23
	v_and_b32_e32 v23, 0xffff0000, v23
	v_lshlrev_b32_e32 v34, 16, v24
	v_and_b32_e32 v35, 0xffff0000, v24
	v_lshlrev_b32_e32 v28, 16, v25
	v_and_b32_e32 v29, 0xffff0000, v25
	v_pk_fma_f32 v[24:25], s[72:73], v[112:113], v[22:23]
	v_pk_fma_f32 v[22:23], s[52:53], v[110:111], v[26:27]
	v_pk_fma_f32 v[28:29], s[72:73], v[108:109], v[28:29]
	v_pk_fma_f32 v[26:27], s[52:53], v[106:107], v[34:35]
	s_mov_b64 s[12:13], -1
	s_and_b64 vcc, exec, s[6:7]
	v_lshl_add_u64 v[30:31], v[30:31], 2, s[54:55]
	s_cbranch_vccnz .LBB0_440
	s_mov_b64 s[12:13], 0
	global_store_dwordx4 v[30:31], v[22:25], off
	global_store_dwordx4 v[30:31], v[26:29], off offset:16

;     __device__ __forceinline__ void operator()(AccRef acc, const pg8::Unit& u, int wr, int wc, int fr, int fq) const {
;     ...
;                     const size_t p = (size_t)row * D + col0 + bj * 128;
;                     const v4u w0 = xw[m][bj];
;                     f32x4 a = {bflo(w0.x), bfhi(w0.x), bflo(w0.y), bfhi(w0.y)}, b = {bflo(w0.z), bfhi(w0.z), bflo(w0.w), bfhi(w0.w)};
;                     a = a + acc[ai][bj][m][0] * scale; b = b + acc[ai][bj][m][1] * scale;
;                     if (outf) { *(f32x4*)(outf + p) = a; *(f32x4*)(outf + p + 4) = b; }
.LBB0_442:
	s_nop 3
	s_nop 0
	v_lshlrev_b32_e32 v22, 16, v18
	v_and_b32_e32 v23, 0xffff0000, v18
	v_lshlrev_b32_e32 v18, 16, v19
	v_and_b32_e32 v19, 0xffff0000, v19
	v_lshlrev_b32_e32 v26, 16, v20
	v_and_b32_e32 v27, 0xffff0000, v20
	v_lshlrev_b32_e32 v24, 16, v21
	v_and_b32_e32 v25, 0xffff0000, v21
	v_pk_fma_f32 v[20:21], s[72:73], v[104:105], v[18:19]
	v_pk_fma_f32 v[18:19], s[52:53], v[102:103], v[22:23]
	v_pk_fma_f32 v[24:25], s[72:73], v[100:101], v[24:25]
	v_pk_fma_f32 v[22:23], s[52:53], v[98:99], v[26:27]
	s_and_b64 vcc, exec, s[6:7]
	s_mov_b64 s[12:13], -1
	s_cbranch_vccnz .LBB0_445
	global_store_dwordx4 v[30:31], v[18:21], off offset:512
	global_store_dwordx4 v[30:31], v[22:25], off offset:528
	s_cbranch_execz .LBB0_446

;     __device__ __forceinline__ void operator()(AccRef acc, const pg8::Unit& u, int wr, int wc, int fr, int fq) const {
;     ...
;                     const size_t p = (size_t)row * D + col0 + bj * 128;
;                     const v4u w0 = xw[m][bj];
;                     f32x4 a = {bflo(w0.x), bfhi(w0.x), bflo(w0.y), bfhi(w0.y)}, b = {bflo(w0.z), bfhi(w0.z), bflo(w0.w), bfhi(w0.w)};
;                     a = a + acc[ai][bj][m][0] * scale; b = b + acc[ai][bj][m][1] * scale;
;                     if (outf) { *(f32x4*)(outf + p) = a; *(f32x4*)(outf + p + 4) = b; }
.LBB0_450:
	v_lshlrev_b64 v[24:25], 10, v[46:47]
	v_lshl_add_u64 v[22:23], v[24:25], 0, v[40:41]
	s_nop 3
	v_lshlrev_b32_e32 v18, 16, v14
	s_waitcnt lgkmcnt(0)
	v_and_b32_e32 v19, 0xffff0000, v14
	v_lshlrev_b32_e32 v14, 16, v15
	v_and_b32_e32 v15, 0xffff0000, v15
	v_lshlrev_b32_e32 v26, 16, v16
	v_and_b32_e32 v27, 0xffff0000, v16
	v_lshlrev_b32_e32 v20, 16, v17
	v_and_b32_e32 v21, 0xffff0000, v17
	v_pk_fma_f32 v[16:17], s[72:73], v[96:97], v[14:15]
	v_pk_fma_f32 v[14:15], s[52:53], v[94:95], v[18:19]
	v_pk_fma_f32 v[20:21], s[72:73], v[92:93], v[20:21]
	v_pk_fma_f32 v[18:19], s[52:53], v[90:91], v[26:27]
	s_mov_b64 s[12:13], -1
	s_and_b64 vcc, exec, s[6:7]
	v_lshl_add_u64 v[22:23], v[22:23], 2, s[54:55]
	s_cbranch_vccnz .LBB0_452
	s_mov_b64 s[12:13], 0
	global_store_dwordx4 v[22:23], v[14:17], off
	global_store_dwordx4 v[22:23], v[18:21], off offset:16

;     __device__ __forceinline__ void operator()(AccRef acc, const pg8::Unit& u, int wr, int wc, int fr, int fq) const {
;     ...
;                     const size_t p = (size_t)row * D + col0 + bj * 128;
;                     const v4u w0 = xw[m][bj];
;                     f32x4 a = {bflo(w0.x), bfhi(w0.x), bflo(w0.y), bfhi(w0.y)}, b = {bflo(w0.z), bfhi(w0.z), bflo(w0.w), bfhi(w0.w)};
;                     a = a + acc[ai][bj][m][0] * scale; b = b + acc[ai][bj][m][1] * scale;
;                     if (outf) { *(f32x4*)(outf + p) = a; *(f32x4*)(outf + p + 4) = b; }
.LBB0_454:
	s_nop 3
	s_nop 0
	v_lshlrev_b32_e32 v14, 16, v10
	v_and_b32_e32 v15, 0xffff0000, v10
	v_lshlrev_b32_e32 v10, 16, v11
	v_and_b32_e32 v11, 0xffff0000, v11
	v_lshlrev_b32_e32 v18, 16, v12
	v_and_b32_e32 v19, 0xffff0000, v12
	v_lshlrev_b32_e32 v16, 16, v13
	v_and_b32_e32 v17, 0xffff0000, v13
	v_pk_fma_f32 v[12:13], s[72:73], v[88:89], v[10:11]
	v_pk_fma_f32 v[10:11], s[52:53], v[86:87], v[14:15]
	v_pk_fma_f32 v[16:17], s[72:73], v[84:85], v[16:17]
	v_pk_fma_f32 v[14:15], s[52:53], v[82:83], v[18:19]
	s_and_b64 vcc, exec, s[6:7]
	s_mov_b64 s[12:13], -1
	s_cbranch_vccnz .LBB0_457
	global_store_dwordx4 v[22:23], v[10:13], off offset:512
	global_store_dwordx4 v[22:23], v[14:17], off offset:528
	s_cbranch_execz .LBB0_458

;     __device__ __forceinline__ void operator()(AccRef acc, const pg8::Unit& u, int wr, int wc, int fr, int fq) const {
;     ...
;                     const size_t p = (size_t)row * D + col0 + bj * 128;
;                     const v4u w0 = xw[m][bj];
;                     f32x4 a = {bflo(w0.x), bfhi(w0.x), bflo(w0.y), bfhi(w0.y)}, b = {bflo(w0.z), bfhi(w0.z), bflo(w0.w), bfhi(w0.w)};
;                     a = a + acc[ai][bj][m][0] * scale; b = b + acc[ai][bj][m][1] * scale;
;                     if (outf) { *(f32x4*)(outf + p) = a; *(f32x4*)(outf + p + 4) = b; }
.LBB0_462:
	v_lshlrev_b64 v[16:17], 10, v[42:43]
	v_lshl_add_u64 v[14:15], v[16:17], 0, v[40:41]
	s_nop 3
	v_lshlrev_b32_e32 v10, 16, v6
	s_waitcnt lgkmcnt(0)
	v_and_b32_e32 v11, 0xffff0000, v6
	v_lshlrev_b32_e32 v6, 16, v7
	v_and_b32_e32 v7, 0xffff0000, v7
	v_lshlrev_b32_e32 v18, 16, v8
	v_and_b32_e32 v19, 0xffff0000, v8
	v_lshlrev_b32_e32 v12, 16, v9
	v_and_b32_e32 v13, 0xffff0000, v9
	v_pk_fma_f32 v[8:9], s[72:73], v[80:81], v[6:7]
	v_pk_fma_f32 v[6:7], s[52:53], v[78:79], v[10:11]
	v_pk_fma_f32 v[12:13], s[72:73], v[76:77], v[12:13]
	v_pk_fma_f32 v[10:11], s[52:53], v[74:75], v[18:19]
	s_mov_b64 s[12:13], -1
	s_and_b64 vcc, exec, s[6:7]
	v_lshl_add_u64 v[14:15], v[14:15], 2, s[54:55]
	s_cbranch_vccnz .LBB0_464
	s_mov_b64 s[12:13], 0
	global_store_dwordx4 v[14:15], v[6:9], off
	global_store_dwordx4 v[14:15], v[10:13], off offset:16
